# attention w-units: once a unit's K/V tiles have landed, each wave touches the next unit's K/V tiles (and Q rows for dilated units) one dword per 128-byte line so they are in L2 when that unit's LDS-DM
# speedup vs baseline: 1.0042x; 1.0042x over previous
; #define LAS __attribute__((address_space(3)))
; __device__ __forceinline__ void attn_unit_w(LAS unsigned char* lds, const AU& u, int tid, int wid, int lane) {
;     const int r = lane & 31, h = lane >> 5;
;     const int qidx = u.q0 + 32 * wid + r;
;     LAS float* lut = (LAS float*)(lds + BW_LUT);
;     for (int i = tid; i < 2 * u.R + 1 + 2 * AT_PAD; i += NTHREADS) { const int j = i - AT_PAD; lut[i] = (j >= 0 && j <= 2 * u.R) ? u.lut[j] : -1e30f; }
;     bf16x8 qf[4];
;     { const bf16_t* qp = u.Q + (size_t)qidx * u.qpitch + 8 * h;
; #pragma unroll
;       for (int ks = 0; ks < 4; ++ks) qf[ks] = *(const bf16x8*)(qp + 16 * ks); }
;     float m = u.m0, l = u.l0;
;     f32x16 o0, o1;
; #pragma unroll
;     for (int i = 0; i < 16; ++i) { o0[i] = 0.f; o1[i] = 0.f; }
;     const int qlo = u.q0 + 32 * wid;
;     int t_lo = (qlo - u.R) >> 6, t_hi = ((qlo + 31 + u.R) >> 6) + 1;
;     t_lo = t_lo < u.kt_lo ? u.kt_lo : t_lo; t_hi = t_hi > u.kt_hi ? u.kt_hi : t_hi;
;     LAS unsigned char* Vw = lds + wid * BW_VBYTES;
;     const int vkey = lane >> 3, vch = lane & 7;
;     bf16x8 kf[8]; u32x4 vr[8];
;     const bf16_t* kbase = u.K1 + (size_t)r * u.k1pitch + 8 * h;
;     const bf16_t* vbase = u.V + (size_t)vkey * u.vpitch + 8 * vch;
;     ...
;     __syncthreads();
;     if (t_lo < t_hi) BW_LOAD(t_lo);
; __global__ void __launch_bounds__(NTHREADS) mega(Args a) {
;     ...
;         for (int ui = bid; ui < 5 * 512; ui += G) {
;             const int kind = ui >> 9, idx = ui & 511;
;             const int bb = idx >> 6, rem = idx & 63, head = rem >> 4, rr = rem & 15;
;             AU u;
;             if (kind == 0) {
;                 const size_t hrow = (size_t)(bb * 4 + head) * SEQ;
;                 u.Q = HB + hrow * 96; u.qpitch = 96; u.K1 = HB + (size_t)T * 384 + hrow * 64; u.k1pitch = 64; u.K2 = KR + (size_t)bb * SEQ * 32; u.k2pitch = 32;
;                 u.V = HB + (size_t)T * 640 + hrow * 64; u.vpitch = 64; u.O = MIX + (size_t)bb * SEQ * 1024 + 512 + head * 64; u.opitch = 1024; u.LSE = nullptr; u.lsepitch = 0; u.lut = nullptr;
;                 u.R = 1 << 20; u.q0 = 256 * rr; u.kt_lo = 0; u.kt_hi = 64; u.sc = 0.10206207261596575f * LOG2E; u.m0 = -1e30f; u.l0 = 0.f;
;                 attn_unit_c(lds, u, tid, wave, lane);
;             } else {
;                 int Ls;
;                 if (kind == 1) {
;                     const bf16_t* hmb = PROJ + HM_OFF;
.LBB0_812:
	s_or_b64 exec, exec, s[36:37]
	s_lshl_b32 s0, s0, 8
	s_add_i32 s12, s0, s65
	v_or_b32_e32 v0, s12, v173
	v_ashrrev_i32_e32 v1, 31, v0
	v_lshlrev_b64 v[0:1], 7, v[0:1]
	v_lshl_add_u64 v[0:1], s[28:29], 0, v[0:1]
	v_lshlrev_b32_e32 v112, 1, v170
	v_lshl_add_u64 v[0:1], v[0:1], 0, v[112:113]
	s_or_b32 s28, s62, s0
	s_addk_i32 s28, 0xc0
	s_lshr_b32 s28, s28, 6
	s_add_i32 s28, s28, 1
	s_min_u32 s29, s28, s63
	s_sub_i32 s28, s12, s62
	s_add_i32 s12, s12, s62
	s_sub_i32 s13, s0, s62
	s_ashr_i32 s12, s12, 6
	s_ashr_i32 s13, s13, 6
	s_ashr_i32 s28, s28, 6
	s_add_i32 s30, s12, 1
	v_mov_b32_e32 v0, s28
	s_cmp_lt_i32 s12, s29
	v_max3_i32 v0, s13, v0, 0
	s_cselect_b32 s29, s30, s29
	v_cmp_gt_i32_e32 vcc, s29, v0
	v_readfirstlane_b32 s28, v0
	v_mov_b32_e32 v15, 0
	s_mov_b32 s70, 0x16401000
	s_waitcnt vmcnt(0) lgkmcnt(0)
	s_barrier
	s_add_i32 s1, s74, s33
	s_lshr_b32 s58, s1, 9
	s_cmp_gt_u32 s58, 4
	s_cbranch_scc1 .Lpf_done
	s_and_b32 s36, s1, 15
	s_bfe_u32 s75, s1, 0x20004
	s_bfe_u32 s99, s1, 0x30006
	s_cmp_eq_u32 s58, 1
	s_cbranch_scc1 .Lpf_a
	s_add_i32 s58, s58, -2
	s_lshl_b32 s100, s58, 1
	s_lshl_b32 s101, 1, s100
	s_add_i32 s101, s101, -1
	s_and_b32 s101, s101, s36
	s_lshl_b32 s26, s99, 14
	s_lshl_b32 s27, s75, 12
	s_or_b32 s26, s26, s27
	s_sub_i32 s27, 12, s100
	s_lshl_b32 s101, s101, s27
	s_add_i32 s26, s26, s101
	s_lshl_b32 s26, s26, 7
	s_mul_i32 s27, s58, 3
	s_lshl_b32 s27, s27, 24
	s_add_u32 s26, s26, s27
	s_add_u32 s26, s26, 0x3000000
	s_add_u32 s34, s51, s26
	s_addc_u32 s35, s56, 0
	s_lshr_b32 s36, s36, s100
	s_lshr_b32 s101, 64, s100
	s_mov_b32 s100, 64
	s_mov_b32 s99, 0x1000000
	s_mov_b32 s75, 1
	s_branch .Lpf_go
.Lpf_a:
	s_lshl_b32 s26, s99, 2
	s_lshr_b32 s27, s75, 1
	s_or_b32 s26, s26, s27
	s_lshl_b32 s26, s26, 19
	s_add_u32 s34, s57, s26
	s_addc_u32 s35, s61, 0
	s_mov_b32 s101, 64
	s_movk_i32 s100, 0x80
	s_mov_b32 s99, 0x100000
	s_mov_b32 s75, 0
.Lpf_go:
	s_lshl_b32 s36, s36, 8
	s_sub_i32 s26, s36, s100
	s_ashr_i32 s26, s26, 6
	s_max_i32 s26, s26, 0
	s_add_i32 s27, s36, s100
	s_addk_i32 s27, 0xc0
	s_lshr_b32 s27, s27, 6
	s_add_i32 s27, s27, 1
	s_min_u32 s27, s27, s101
	s_sub_i32 s27, s27, s26
	s_lshr_b32 s58, s65, 5
	v_and_b32_e32 v81, 63, v171
	v_lshlrev_b32_e32 v81, 7, v81
	s_cmp_lt_u32 s58, s27
	s_cbranch_scc0 .Lpf_q
	s_add_i32 s26, s26, s58
	s_lshl_b32 s26, s26, 13
	s_add_u32 s34, s34, s26
	s_addc_u32 s35, s35, 0
	global_load_dword v80, v81, s[34:35]
	s_add_u32 s34, s34, s99
	s_addc_u32 s35, s35, 0
	global_load_dword v80, v81, s[34:35]
	s_branch .Lpf_done
.Lpf_q:
	s_cmp_eq_u32 s75, 0
	s_cbranch_scc1 .Lpf_done
	s_cmp_lt_u32 s58, 6
	s_cbranch_scc1 .Lpf_done
	s_add_i32 s58, s58, -6
	s_lshl_b32 s58, s58, 14
	s_lshl_b32 s26, s36, 7
	s_add_i32 s26, s26, s58
	s_sub_u32 s34, s34, 0x1000000
	s_subb_u32 s35, s35, 0
	s_add_u32 s34, s34, s26
	s_addc_u32 s35, s35, 0
	global_load_dword v80, v81, s[34:35]
	s_add_u32 s34, s34, 0x2000
	s_addc_u32 s35, s35, 0
	global_load_dword v80, v81, s[34:35]
.Lpf_done:
	s_cbranch_vccz .LBB0_818
	v_add_lshl_u32 v40, v202, s0, 2
	s_lshl_b32 s4, s28, 8
	s_lshl_b32 s5, s62, 2
	s_add_i32 s4, s4, s5
	v_sub_u32_e32 v40, s4, v40
	v_add_u32_e32 v112, v207, v40
	s_max_i32 s98, s13, 0
	s_sub_i32 s98, s28, s98
	s_lshl_b32 s98, s98, 13
	v_add_u32_e32 v221, s98, v186
	v_and_b32_e32 v222, 63, v171
	v_lshrrev_b32_e32 v223, 2, v222
	v_and_b32_e32 v223, 3, v223
	v_lshrrev_b32_e32 v224, 5, v222
	v_lshl_or_b32 v223, v224, 2, v223
	v_and_b32_e32 v224, 8, v222
	v_lshlrev_b32_e32 v224, 3, v224
	v_xor_b32_e32 v224, v224, v200
	v_lshl_or_b32 v222, v223, 7, v224
	s_add_i32 s98, s98, 0x10000
	v_add_u32_e32 v222, s98, v222
	v_xor_b32_e32 v223, 64, v222
	ds_read_b128 v[114:117], v221
	ds_read_b128 v[118:121], v221 offset:1024
	ds_read_b128 v[126:129], v221 offset:4096
	ds_read_b128 v[130:133], v221 offset:5120
	ds_read_b128 v[122:125], v221 offset:2048
	ds_read_b128 v[134:137], v221 offset:3072
	ds_read_b128 v[138:141], v221 offset:6144
	ds_read_b128 v[142:145], v221 offset:7168
	v_readlane_b32 s62, v255, 34
	v_mov_b32_e32 v187, s59
	v_mov_b32_e32 v0, 0
	v_mov_b32_e32 v1, v0
	v_mov_b32_e32 v2, v0
	v_mov_b32_e32 v3, v0
	v_mov_b32_e32 v4, v0
	v_mov_b32_e32 v5, v0
	v_mov_b32_e32 v6, v0
	v_mov_b32_e32 v7, v0
	v_mov_b32_e32 v8, v0
	v_mov_b32_e32 v9, v0
	v_mov_b32_e32 v10, v0
	v_mov_b32_e32 v11, v0
	v_mov_b32_e32 v12, v0
	v_mov_b32_e32 v13, v0
	v_mov_b32_e32 v14, v0
	v_mov_b32_e32 v15, v0
	v_mov_b32_e32 v16, v0
	v_mov_b32_e32 v17, v0
	v_mov_b32_e32 v18, v0
	v_mov_b32_e32 v19, v0
	v_mov_b32_e32 v20, v0
	v_mov_b32_e32 v21, v0
	v_mov_b32_e32 v22, v0
	v_mov_b32_e32 v23, v0
	v_mov_b32_e32 v24, v0
	v_mov_b32_e32 v25, v0
	v_mov_b32_e32 v26, v0
	v_mov_b32_e32 v27, v0
	v_mov_b32_e32 v28, v0
	v_mov_b32_e32 v29, v0
	v_mov_b32_e32 v30, v0
	v_mov_b32_e32 v31, v0
	v_readlane_b32 s63, v255, 35
